# v45 + back-edge rotation in both attention loops (loop-carried SALU moved ahead of the end-of-iteration barrier)
# baseline (speedup 1.0000x reference)
; __device__ __forceinline__ void attn_mla_unit(LAS unsigned char* lds, const bf16_t* __restrict__ QM, const bf16_t* __restrict__ Kb, const bf16_t* __restrict__ KR, const bf16_t* __restrict__ VT, bf16_t* O,
;                                               int qrow0, int b, int h, int ntiles) {
;     ...
;     int t = 1;
;     for (; t + 1 < ntiles; t += 2) { M_STEP(pB0, pB1, pA0, pA1); M_STEP(pA0, pA1, pB0, pB1); }
.LBB0_793:
	s_add_i32 s16, s15, 1
	s_cmp_lg_u32 s15, 2
	s_cselect_b32 s15, s16, 0
	s_xor_b32 s10, s10, 2
	s_add_i32 s14, s14, 2
	s_cmp_lt_u32 s14, s2
	s_waitcnt vmcnt(3) lgkmcnt(0)
	s_barrier
	s_cbranch_scc1 .LBB0_751
	s_branch .LBB0_818

; __device__ __forceinline__ void attn_diff_unit(LAS unsigned char* lds, const bf16_t* __restrict__ Q, const bf16_t* __restrict__ Kb, const bf16_t* __restrict__ VT, bf16_t* O,
;                                                int qrow0, int b, int h, int ntiles, float lam, const float* subln_g) {
;     ...
;     int t = 1;
;     for (; t + 1 < ntiles; t += 2) { D_STEP(pB0, pB1, pA0, pA1); D_STEP(pA0, pA1, pB0, pB1); }
.LBB0_1118:
	s_add_i32 s29, s28, 1
	s_cmp_lg_u32 s28, 2
	s_cselect_b32 s28, s29, 0
	s_xor_b32 s13, s13, 2
	s_add_i32 s17, s17, 2
	s_cmp_lt_u32 s17, s15
	s_waitcnt vmcnt(5) lgkmcnt(0)
	s_barrier
	s_cbranch_scc1 .LBB0_1098
	s_branch .LBB0_1123
